# no per-phase priority flips + one static s_setprio 1 for waves 4-7 at kernel entry
# baseline (speedup 1.0000x reference)
; #define LAS __attribute__((address_space(3)))
; __global__ void __launch_bounds__(NTHR, 2) fwd_megakernel(Args a) {
;     extern __shared__ __attribute__((aligned(16))) unsigned char lds_raw[];
;     LAS unsigned char* lds = (LAS unsigned char*)lds_raw;
;     cg::grid_group grid = cg::this_grid();
;     const int G = gridDim.x, bx = blockIdx.x, lo = a.ph_lo, hi = a.ph_hi;
;     volatile LAS unsigned* bst = (volatile LAS unsigned*)(lds + LDS_BYTES - 16);
;     if (threadIdx.x == 0) { bst[0] = 0u; bst[1] = 0u; }
;     __syncthreads();
;     const XcdBarrier xbar = xcd_barrier_post((unsigned*)(a.ws + WS_BAR), bst);
_Z14fwd_megakernel4Args:
	s_load_dwordx16 s[36:51], s[0:1], 0x80
	s_load_dwordx4 s[68:71], s[0:1], 0xc0
	s_load_dword s3, s[0:1], 0xd0
	s_add_u32 s4, s0, 0xc8
	s_addc_u32 s5, s1, 0
	v_and_b32_e32 v176, 0x3ff, v0
	v_cmp_eq_u32_e64 s[8:9], 0, v176
	s_waitcnt lgkmcnt(0)
	v_readfirstlane_b32 s98, v176
	s_nop 3
	s_lshr_b32 s98, s98, 6
	s_cmp_lt_u32 s98, 4
	s_cbranch_scc1 .Lprio_done
	s_setprio 1
.Lprio_done:
	v_writelane_b32 v254, s3, 0
	s_mov_b64 s[6:7], exec
	v_writelane_b32 v254, s8, 1
	s_nop 1
	v_writelane_b32 v254, s9, 2
	s_and_b64 s[8:9], s[6:7], s[8:9]
	s_mov_b64 exec, s[8:9]
	s_cbranch_execz .LBB0_2
	s_add_i32 s3, 0, 0x23ff0
	v_mov_b32_e32 v1, 0
	v_mov_b32_e32 v2, s3
	s_add_i32 s3, 0, 0x23ff4
	ds_write_b32 v2, v1
	v_mov_b32_e32 v2, s3
	ds_write_b32 v2, v1
